# v33 plus dead per-row epilogue precomputations (14 VALU incl. 5 mul_lo per tile) removed
# speedup vs baseline: 1.0038x; 1.0006x over previous
; DI unsigned pk2(float lo, float hi) { f32x2 v = {lo, hi}; bf16v2 b = __builtin_convertvector(v, bf16v2); return __builtin_bit_cast(unsigned, b); }
; DI float silu_f(float x) { return x * __builtin_amdgcn_rcpf(1.f + __expf(-x)); }
;     DI void operator()(const f32x4 (&acc)[2][2][4][2], const Unit& u, int wr, int wc, int fr, int fq) const {
;         const int row0 = u.pm * BM + wr * 64 + fr, col0 = u.pn * HALF + wc * 32 + 8 * fq;
; #pragma unroll
;         for (int ai = 0; ai < 2; ++ai)
; #pragma unroll
;             for (int m = 0; m < 4; ++m) { bf16_t* rowp = O + (size_t)(row0 + ai * HALF + m * 16) * ldc + col0;
;                 float r[8];
; #pragma unroll
;                 for (int n = 0; n < 2; ++n)
; #pragma unroll
;                     for (int e = 0; e < 4; ++e) { const float g = acc[ai][0][m][n][e], up = acc[ai][1][m][n][e]; r[n * 4 + e] = silu_f(g) * up; }
;                 u32x4 o; o.x = pk2(r[0], r[1]); o.y = pk2(r[2], r[3]); o.z = pk2(r[4], r[5]); o.w = pk2(r[6], r[7]);
;                 *(u32x4*)rowp = o; }
.Lgemm_epi:
	v_lshl_add_u32 v140, s80, 8, v145
	v_ashrrev_i32_e32 v138, 31, v140
	v_mul_lo_u32 v157, s78, v138
	v_mul_lo_u32 v141, s79, v140
	v_mad_u64_u32 v[138:139], s[18:19], s78, v140, 0
	v_add3_u32 v139, v139, v157, v141
	s_mov_b64 s[18:19], -1
	s_andn2_b64 vcc, exec, s[14:15]
	s_cbranch_vccnz .LBB0_746
	s_lshl_b32 s100, s78, 5
	s_mov_b32 s101, 0
	v_mul_f32_e32 v140, 0xbfb8aa3b, v24
	v_mul_f32_e32 v141, 0xbfb8aa3b, v25
	v_mul_f32_e32 v166, 0xbfb8aa3b, v26
	v_mul_f32_e32 v167, 0xbfb8aa3b, v27
	v_mul_f32_e32 v168, 0xbfb8aa3b, v28
	v_mul_f32_e32 v169, 0xbfb8aa3b, v29
	v_exp_f32_e32 v140, v140
	v_exp_f32_e32 v141, v141
	v_exp_f32_e32 v166, v166
	v_exp_f32_e32 v167, v167
	v_exp_f32_e32 v168, v168
	v_exp_f32_e32 v169, v169
	v_mul_f32_e32 v170, 0xbfb8aa3b, v30
	v_mul_f32_e32 v171, 0xbfb8aa3b, v31
	v_add_f32_e32 v140, 1.0, v140
	v_add_f32_e32 v141, 1.0, v141
	v_add_f32_e32 v166, 1.0, v166
	v_add_f32_e32 v167, 1.0, v167
	v_add_f32_e32 v168, 1.0, v168
	v_add_f32_e32 v169, 1.0, v169
	v_exp_f32_e32 v170, v170
	v_exp_f32_e32 v171, v171
	v_rcp_f32_e32 v164, v140
	v_rcp_f32_e32 v165, v141
	v_rcp_f32_e32 v166, v166
	v_rcp_f32_e32 v167, v167
	v_rcp_f32_e32 v168, v168
	v_rcp_f32_e32 v169, v169
	v_add_f32_e32 v170, 1.0, v170
	v_add_f32_e32 v171, 1.0, v171
	v_pk_mul_f32 v[164:165], v[24:25], v[164:165]
	v_pk_mul_f32 v[166:167], v[26:27], v[166:167]
	v_rcp_f32_e32 v170, v170
	v_rcp_f32_e32 v171, v171
	v_pk_mul_f32 v[168:169], v[28:29], v[168:169]
	v_pk_mul_f32 v[164:165], v[164:165], v[88:89]
	v_pk_mul_f32 v[166:167], v[166:167], v[90:91]
	v_pk_mul_f32 v[168:169], v[168:169], v[96:97]
	v_cvt_pk_bf16_f32 v164, v164, v165
	v_cvt_pk_bf16_f32 v165, v166, v167
	v_cvt_pk_bf16_f32 v166, v168, v169
	v_mul_f32_e32 v168, 0xbfb8aa3b, v16
	v_mul_f32_e32 v169, 0xbfb8aa3b, v17
	v_lshl_or_b32 v140, s77, 7, v147
	v_readlane_b32 s18, v255, 30
	v_exp_f32_e32 v168, v168
	v_exp_f32_e32 v169, v169
	v_ashrrev_i32_e32 v141, 31, v140
	v_readlane_b32 s19, v255, 31
	v_pk_mul_f32 v[170:171], v[30:31], v[170:171]
	s_nop 0
	v_lshl_add_u64 v[140:141], v[140:141], 1, s[18:19]
	v_pk_mul_f32 v[170:171], v[170:171], v[98:99]
	v_lshl_add_u64 v[174:175], v[138:139], 1, v[140:141]
	v_cvt_pk_bf16_f32 v167, v170, v171
	global_store_dwordx4 v[174:175], v[164:167], off
	s_nop 1
	v_mul_f32_e32 v170, 0xbfb8aa3b, v20
	v_mul_f32_e32 v171, 0xbfb8aa3b, v21
	v_add_f32_e32 v164, 1.0, v168
	v_add_f32_e32 v165, 1.0, v169
	v_mul_f32_e32 v168, 0xbfb8aa3b, v18
	v_mul_f32_e32 v169, 0xbfb8aa3b, v19
	v_exp_f32_e32 v168, v168
	v_exp_f32_e32 v169, v169
	v_mul_f32_e32 v172, 0xbfb8aa3b, v22
	v_mul_f32_e32 v173, 0xbfb8aa3b, v23
	v_add_f32_e32 v168, 1.0, v168
	v_add_f32_e32 v169, 1.0, v169
	v_exp_f32_e32 v170, v170
	v_exp_f32_e32 v171, v171
	v_exp_f32_e32 v172, v172
	v_exp_f32_e32 v173, v173
	v_rcp_f32_e32 v164, v164
	v_rcp_f32_e32 v165, v165
	v_rcp_f32_e32 v168, v168
	v_rcp_f32_e32 v169, v169
	v_add_f32_e32 v170, 1.0, v170
	v_add_f32_e32 v171, 1.0, v171
	v_add_f32_e32 v172, 1.0, v172
	v_add_f32_e32 v173, 1.0, v173
	v_pk_mul_f32 v[164:165], v[16:17], v[164:165]
	v_pk_mul_f32 v[168:169], v[18:19], v[168:169]
	v_rcp_f32_e32 v170, v170
	v_rcp_f32_e32 v171, v171
	v_rcp_f32_e32 v172, v172
	v_rcp_f32_e32 v173, v173
	v_pk_mul_f32 v[164:165], v[164:165], v[80:81]
	v_pk_mul_f32 v[168:169], v[168:169], v[82:83]
	v_cvt_pk_bf16_f32 v164, v164, v165
	v_cvt_pk_bf16_f32 v165, v168, v169
	v_mul_f32_e32 v168, 0xbfb8aa3b, v8
	v_mul_f32_e32 v169, 0xbfb8aa3b, v9
	v_exp_f32_e32 v168, v168
	v_exp_f32_e32 v169, v169
	v_pk_mul_f32 v[170:171], v[20:21], v[170:171]
	v_pk_mul_f32 v[172:173], v[22:23], v[172:173]
	v_pk_mul_f32 v[170:171], v[170:171], v[84:85]
	v_pk_mul_f32 v[172:173], v[172:173], v[86:87]
	v_lshl_add_u64 v[174:175], v[174:175], 0, s[100:101]
	v_cvt_pk_bf16_f32 v166, v170, v171
	v_cvt_pk_bf16_f32 v167, v172, v173
	global_store_dwordx4 v[174:175], v[164:167], off
	s_nop 1
	v_mul_f32_e32 v170, 0xbfb8aa3b, v12
	v_mul_f32_e32 v171, 0xbfb8aa3b, v13
	v_add_f32_e32 v164, 1.0, v168
	v_add_f32_e32 v165, 1.0, v169
	v_mul_f32_e32 v168, 0xbfb8aa3b, v10
	v_mul_f32_e32 v169, 0xbfb8aa3b, v11
	v_exp_f32_e32 v168, v168
	v_exp_f32_e32 v169, v169
	v_mul_f32_e32 v172, 0xbfb8aa3b, v14
	v_mul_f32_e32 v173, 0xbfb8aa3b, v15
	v_add_f32_e32 v168, 1.0, v168
	v_add_f32_e32 v169, 1.0, v169
	v_exp_f32_e32 v170, v170
	v_exp_f32_e32 v171, v171
	v_exp_f32_e32 v172, v172
	v_exp_f32_e32 v173, v173
	v_rcp_f32_e32 v164, v164
	v_rcp_f32_e32 v165, v165
	v_rcp_f32_e32 v168, v168
	v_rcp_f32_e32 v169, v169
	v_add_f32_e32 v170, 1.0, v170
	v_add_f32_e32 v171, 1.0, v171
	v_add_f32_e32 v172, 1.0, v172
	v_add_f32_e32 v173, 1.0, v173
	v_pk_mul_f32 v[164:165], v[8:9], v[164:165]
	v_pk_mul_f32 v[168:169], v[10:11], v[168:169]
	v_rcp_f32_e32 v170, v170
	v_rcp_f32_e32 v171, v171
	v_rcp_f32_e32 v172, v172
	v_rcp_f32_e32 v173, v173
	v_pk_mul_f32 v[164:165], v[164:165], v[72:73]
	v_pk_mul_f32 v[168:169], v[168:169], v[74:75]
	v_cvt_pk_bf16_f32 v164, v164, v165
	v_cvt_pk_bf16_f32 v165, v168, v169
	v_mul_f32_e32 v168, 0xbfb8aa3b, v0
	v_mul_f32_e32 v169, 0xbfb8aa3b, v1
	v_exp_f32_e32 v168, v168
	v_exp_f32_e32 v169, v169
	v_pk_mul_f32 v[170:171], v[12:13], v[170:171]
	v_pk_mul_f32 v[172:173], v[14:15], v[172:173]
	v_pk_mul_f32 v[170:171], v[170:171], v[76:77]
	v_pk_mul_f32 v[172:173], v[172:173], v[78:79]
	v_lshl_add_u64 v[174:175], v[174:175], 0, s[100:101]
	v_cvt_pk_bf16_f32 v166, v170, v171
	v_cvt_pk_bf16_f32 v167, v172, v173
	global_store_dwordx4 v[174:175], v[164:167], off
	s_nop 1
	v_mul_f32_e32 v170, 0xbfb8aa3b, v4
	v_mul_f32_e32 v171, 0xbfb8aa3b, v5
	v_add_f32_e32 v164, 1.0, v168
	v_add_f32_e32 v165, 1.0, v169
	v_mul_f32_e32 v168, 0xbfb8aa3b, v2
	v_mul_f32_e32 v169, 0xbfb8aa3b, v3
; DI unsigned pk2(float lo, float hi) { f32x2 v = {lo, hi}; bf16v2 b = __builtin_convertvector(v, bf16v2); return __builtin_bit_cast(unsigned, b); }
; DI float silu_f(float x) { return x * __builtin_amdgcn_rcpf(1.f + __expf(-x)); }
;     DI void operator()(const f32x4 (&acc)[2][2][4][2], const Unit& u, int wr, int wc, int fr, int fq) const {
;     ...
;             for (int m = 0; m < 4; ++m) { bf16_t* rowp = O + (size_t)(row0 + ai * HALF + m * 16) * ldc + col0;
;                 float r[8];
; #pragma unroll
;                 for (int n = 0; n < 2; ++n)
; #pragma unroll
;                     for (int e = 0; e < 4; ++e) { const float g = acc[ai][0][m][n][e], up = acc[ai][1][m][n][e]; r[n * 4 + e] = silu_f(g) * up; }
;                 u32x4 o; o.x = pk2(r[0], r[1]); o.y = pk2(r[2], r[3]); o.z = pk2(r[4], r[5]); o.w = pk2(r[6], r[7]);
;                 *(u32x4*)rowp = o; }
	v_mul_f32_e32 v172, 0xbfb8aa3b, v6
	v_mul_f32_e32 v173, 0xbfb8aa3b, v7
	v_exp_f32_e32 v168, v168
	v_exp_f32_e32 v169, v169
	v_exp_f32_e32 v170, v170
	v_exp_f32_e32 v171, v171
	v_exp_f32_e32 v172, v172
	v_exp_f32_e32 v173, v173
	v_add_f32_e32 v168, 1.0, v168
	v_add_f32_e32 v169, 1.0, v169
	v_add_f32_e32 v170, 1.0, v170
	v_add_f32_e32 v171, 1.0, v171
	v_add_f32_e32 v172, 1.0, v172
	v_add_f32_e32 v173, 1.0, v173
	v_rcp_f32_e32 v164, v164
	v_rcp_f32_e32 v165, v165
	v_rcp_f32_e32 v168, v168
	v_rcp_f32_e32 v169, v169
	v_rcp_f32_e32 v170, v170
	v_rcp_f32_e32 v171, v171
	v_rcp_f32_e32 v172, v172
	v_rcp_f32_e32 v173, v173
	v_pk_mul_f32 v[164:165], v[0:1], v[164:165]
	v_pk_mul_f32 v[168:169], v[2:3], v[168:169]
	v_pk_mul_f32 v[170:171], v[4:5], v[170:171]
	v_pk_mul_f32 v[172:173], v[6:7], v[172:173]
	v_pk_mul_f32 v[164:165], v[164:165], v[56:57]
	v_pk_mul_f32 v[168:169], v[168:169], v[58:59]
	v_pk_mul_f32 v[170:171], v[170:171], v[64:65]
	v_pk_mul_f32 v[172:173], v[172:173], v[66:67]
	v_lshl_add_u64 v[174:175], v[174:175], 0, s[100:101]
	v_cvt_pk_bf16_f32 v164, v164, v165
	v_cvt_pk_bf16_f32 v165, v168, v169
	v_cvt_pk_bf16_f32 v166, v170, v171
	v_cvt_pk_bf16_f32 v167, v172, v173
	global_store_dwordx4 v[174:175], v[164:167], off
	s_nop 1
	v_mul_f32_e32 v169, 0xbfb8aa3b, v63
	v_mul_f32_e32 v164, 0xbfb8aa3b, v60
	v_mul_f32_e32 v165, 0xbfb8aa3b, v61
	v_mul_f32_e32 v168, 0xbfb8aa3b, v62
	v_mul_f32_e32 v170, 0xbfb8aa3b, v68
	v_mul_f32_e32 v171, 0xbfb8aa3b, v69
	v_mul_f32_e32 v172, 0xbfb8aa3b, v70
	v_mul_f32_e32 v173, 0xbfb8aa3b, v71
	v_exp_f32_e32 v164, v164
	v_exp_f32_e32 v165, v165
	v_exp_f32_e32 v168, v168
	v_exp_f32_e32 v169, v169
	v_exp_f32_e32 v170, v170
	v_exp_f32_e32 v171, v171
	v_exp_f32_e32 v172, v172
	v_exp_f32_e32 v173, v173
	v_add_f32_e32 v164, 1.0, v164
	v_add_f32_e32 v165, 1.0, v165
	v_add_f32_e32 v168, 1.0, v168
	v_add_f32_e32 v169, 1.0, v169
	v_add_f32_e32 v170, 1.0, v170
	v_add_f32_e32 v171, 1.0, v171
	v_add_f32_e32 v172, 1.0, v172
	v_add_f32_e32 v173, 1.0, v173
	v_rcp_f32_e32 v164, v164
	v_rcp_f32_e32 v165, v165
	v_rcp_f32_e32 v168, v168
	v_rcp_f32_e32 v169, v169
	v_rcp_f32_e32 v170, v170
	v_rcp_f32_e32 v171, v171
	v_rcp_f32_e32 v172, v172
	v_rcp_f32_e32 v173, v173
	v_pk_mul_f32 v[164:165], v[60:61], v[164:165]
	v_pk_mul_f32 v[168:169], v[62:63], v[168:169]
	v_pk_mul_f32 v[170:171], v[68:69], v[170:171]
	v_pk_mul_f32 v[172:173], v[70:71], v[172:173]
	v_pk_mul_f32 v[164:165], v[164:165], v[120:121]
	v_pk_mul_f32 v[168:169], v[168:169], v[122:123]
	v_pk_mul_f32 v[170:171], v[170:171], v[124:125]
	v_pk_mul_f32 v[172:173], v[172:173], v[126:127]
	s_mul_i32 vcc_lo, s78, 0xa0
	s_mov_b32 vcc_hi, 0
	v_lshl_add_u64 v[174:175], v[174:175], 0, vcc
	v_cvt_pk_bf16_f32 v164, v164, v165
	v_cvt_pk_bf16_f32 v165, v168, v169
	v_cvt_pk_bf16_f32 v166, v170, v171
	v_cvt_pk_bf16_f32 v167, v172, v173
	global_store_dwordx4 v[174:175], v[164:167], off
	s_nop 1
	v_mul_f32_e32 v169, 0xbfb8aa3b, v51
	v_mul_f32_e32 v164, 0xbfb8aa3b, v48
	v_mul_f32_e32 v165, 0xbfb8aa3b, v49
	v_mul_f32_e32 v168, 0xbfb8aa3b, v50
	v_mul_f32_e32 v170, 0xbfb8aa3b, v52
	v_mul_f32_e32 v171, 0xbfb8aa3b, v53
	v_mul_f32_e32 v172, 0xbfb8aa3b, v54
	v_mul_f32_e32 v173, 0xbfb8aa3b, v55
	v_exp_f32_e32 v164, v164
	v_exp_f32_e32 v165, v165
	v_exp_f32_e32 v168, v168
	v_exp_f32_e32 v169, v169
	v_exp_f32_e32 v170, v170
	v_exp_f32_e32 v171, v171
	v_exp_f32_e32 v172, v172
	v_exp_f32_e32 v173, v173
	v_add_f32_e32 v164, 1.0, v164
	v_add_f32_e32 v165, 1.0, v165
	v_add_f32_e32 v168, 1.0, v168
	v_add_f32_e32 v169, 1.0, v169
	v_add_f32_e32 v170, 1.0, v170
	v_add_f32_e32 v171, 1.0, v171
	v_add_f32_e32 v172, 1.0, v172
	v_add_f32_e32 v173, 1.0, v173
	v_rcp_f32_e32 v164, v164
	v_rcp_f32_e32 v165, v165
	v_rcp_f32_e32 v168, v168
	v_rcp_f32_e32 v169, v169
	v_rcp_f32_e32 v170, v170
	v_rcp_f32_e32 v171, v171
	v_rcp_f32_e32 v172, v172
	v_rcp_f32_e32 v173, v173
; DI unsigned pk2(float lo, float hi) { f32x2 v = {lo, hi}; bf16v2 b = __builtin_convertvector(v, bf16v2); return __builtin_bit_cast(unsigned, b); }
; DI float silu_f(float x) { return x * __builtin_amdgcn_rcpf(1.f + __expf(-x)); }
;     DI void operator()(const f32x4 (&acc)[2][2][4][2], const Unit& u, int wr, int wc, int fr, int fq) const {
;     ...
;             for (int m = 0; m < 4; ++m) { bf16_t* rowp = O + (size_t)(row0 + ai * HALF + m * 16) * ldc + col0;
;                 float r[8];
; #pragma unroll
;                 for (int n = 0; n < 2; ++n)
; #pragma unroll
;                     for (int e = 0; e < 4; ++e) { const float g = acc[ai][0][m][n][e], up = acc[ai][1][m][n][e]; r[n * 4 + e] = silu_f(g) * up; }
;                 u32x4 o; o.x = pk2(r[0], r[1]); o.y = pk2(r[2], r[3]); o.z = pk2(r[4], r[5]); o.w = pk2(r[6], r[7]);
;                 *(u32x4*)rowp = o; }
	v_pk_mul_f32 v[164:165], v[48:49], v[164:165]
	v_pk_mul_f32 v[168:169], v[50:51], v[168:169]
	v_pk_mul_f32 v[170:171], v[52:53], v[170:171]
	v_pk_mul_f32 v[172:173], v[54:55], v[172:173]
	v_pk_mul_f32 v[164:165], v[164:165], v[112:113]
	v_pk_mul_f32 v[168:169], v[168:169], v[114:115]
	v_pk_mul_f32 v[170:171], v[170:171], v[116:117]
	v_pk_mul_f32 v[172:173], v[172:173], v[118:119]
	v_lshl_add_u64 v[174:175], v[174:175], 0, s[100:101]
	v_cvt_pk_bf16_f32 v164, v164, v165
	v_cvt_pk_bf16_f32 v165, v168, v169
	v_cvt_pk_bf16_f32 v166, v170, v171
	v_cvt_pk_bf16_f32 v167, v172, v173
	global_store_dwordx4 v[174:175], v[164:167], off
	s_nop 1
	v_mul_f32_e32 v170, 0xbfb8aa3b, v44
	v_mul_f32_e32 v164, 0xbfb8aa3b, v40
	v_mul_f32_e32 v165, 0xbfb8aa3b, v41
	v_mul_f32_e32 v168, 0xbfb8aa3b, v42
	v_mul_f32_e32 v169, 0xbfb8aa3b, v43
	v_mul_f32_e32 v171, 0xbfb8aa3b, v45
	v_mul_f32_e32 v172, 0xbfb8aa3b, v46
	v_mul_f32_e32 v173, 0xbfb8aa3b, v47
	v_exp_f32_e32 v164, v164
	v_exp_f32_e32 v165, v165
	v_exp_f32_e32 v168, v168
	v_exp_f32_e32 v169, v169
	v_exp_f32_e32 v170, v170
	v_exp_f32_e32 v171, v171
	v_exp_f32_e32 v172, v172
	v_exp_f32_e32 v173, v173
	v_add_f32_e32 v164, 1.0, v164
	v_add_f32_e32 v165, 1.0, v165
	v_add_f32_e32 v168, 1.0, v168
	v_add_f32_e32 v169, 1.0, v169
	v_add_f32_e32 v170, 1.0, v170
	v_add_f32_e32 v171, 1.0, v171
	v_add_f32_e32 v172, 1.0, v172
	v_add_f32_e32 v173, 1.0, v173
	v_rcp_f32_e32 v164, v164
	v_rcp_f32_e32 v165, v165
	v_rcp_f32_e32 v168, v168
	v_rcp_f32_e32 v169, v169
	v_rcp_f32_e32 v170, v170
	v_rcp_f32_e32 v171, v171
	v_rcp_f32_e32 v172, v172
	v_rcp_f32_e32 v173, v173
	v_pk_mul_f32 v[164:165], v[40:41], v[164:165]
	v_pk_mul_f32 v[168:169], v[42:43], v[168:169]
	v_pk_mul_f32 v[170:171], v[44:45], v[170:171]
	v_pk_mul_f32 v[172:173], v[46:47], v[172:173]
	v_pk_mul_f32 v[164:165], v[164:165], v[104:105]
	v_pk_mul_f32 v[168:169], v[168:169], v[106:107]
	v_pk_mul_f32 v[170:171], v[170:171], v[108:109]
	v_pk_mul_f32 v[172:173], v[172:173], v[110:111]
	v_lshl_add_u64 v[174:175], v[174:175], 0, s[100:101]
	v_cvt_pk_bf16_f32 v164, v164, v165
	v_cvt_pk_bf16_f32 v165, v168, v169
	v_cvt_pk_bf16_f32 v166, v170, v171
	v_cvt_pk_bf16_f32 v167, v172, v173
	global_store_dwordx4 v[174:175], v[164:167], off
	s_nop 1
	v_mul_f32_e32 v170, 0xbfb8aa3b, v36
	v_mul_f32_e32 v164, 0xbfb8aa3b, v32
	v_mul_f32_e32 v165, 0xbfb8aa3b, v33
	v_mul_f32_e32 v168, 0xbfb8aa3b, v34
	v_mul_f32_e32 v169, 0xbfb8aa3b, v35
	v_mul_f32_e32 v171, 0xbfb8aa3b, v37
	v_mul_f32_e32 v172, 0xbfb8aa3b, v38
	v_mul_f32_e32 v173, 0xbfb8aa3b, v39
	v_exp_f32_e32 v164, v164
	v_exp_f32_e32 v165, v165
	v_exp_f32_e32 v168, v168
	v_exp_f32_e32 v169, v169
	v_exp_f32_e32 v170, v170
	v_exp_f32_e32 v171, v171
	v_exp_f32_e32 v172, v172
	v_exp_f32_e32 v173, v173
	v_add_f32_e32 v164, 1.0, v164
	v_add_f32_e32 v165, 1.0, v165
	v_add_f32_e32 v168, 1.0, v168
	v_add_f32_e32 v169, 1.0, v169
	v_add_f32_e32 v170, 1.0, v170
	v_add_f32_e32 v171, 1.0, v171
	v_add_f32_e32 v172, 1.0, v172
	v_add_f32_e32 v173, 1.0, v173
	v_rcp_f32_e32 v164, v164
	v_rcp_f32_e32 v165, v165
	v_rcp_f32_e32 v168, v168
	v_rcp_f32_e32 v169, v169
	v_rcp_f32_e32 v170, v170
	v_rcp_f32_e32 v171, v171
	v_rcp_f32_e32 v172, v172
	v_rcp_f32_e32 v173, v173
	v_pk_mul_f32 v[164:165], v[32:33], v[164:165]
	v_pk_mul_f32 v[168:169], v[34:35], v[168:169]
	v_pk_mul_f32 v[170:171], v[36:37], v[170:171]
	v_pk_mul_f32 v[172:173], v[38:39], v[172:173]
	v_pk_mul_f32 v[164:165], v[164:165], v[92:93]
	v_pk_mul_f32 v[168:169], v[168:169], v[94:95]
	v_pk_mul_f32 v[170:171], v[170:171], v[100:101]
	v_pk_mul_f32 v[172:173], v[172:173], v[102:103]
	v_lshl_add_u64 v[174:175], v[174:175], 0, s[100:101]
	v_cvt_pk_bf16_f32 v164, v164, v165
	v_cvt_pk_bf16_f32 v165, v168, v169
	v_cvt_pk_bf16_f32 v166, v170, v171
	v_cvt_pk_bf16_f32 v167, v172, v173
	global_store_dwordx4 v[174:175], v[164:167], off
	s_nop 1
	s_cbranch_execnz .LBB0_748
	s_branch .LBB0_747
